# grid barrier: the last XCD leader fans the release out to every per-XCD XGEN word itself (no relay hop, 31 pollers per line instead of 256 on TOPGEN); early arrival invalidate kept
# speedup vs baseline: 1.0045x; 1.0045x over previous
; __device__ __forceinline__ unsigned xb_ld(unsigned* p)              { return __hip_atomic_load(p, __ATOMIC_RELAXED, __HIP_MEMORY_SCOPE_AGENT); }
; __device__ __forceinline__ unsigned xb_add(unsigned* p, unsigned v) { return __hip_atomic_fetch_add(p, v, __ATOMIC_RELAXED, __HIP_MEMORY_SCOPE_AGENT); }
; #define XB_SPIN(cond, bar) do { unsigned _sp = 0; while (cond) { __builtin_amdgcn_s_sleep(1); \
;     if ((++_sp & 255u) == 0u) { if (xb_ld(&(bar)[XB_TMO])) break; if (_sp > XB_SPIN_CAP) { atomicAdd(&(bar)[XB_TMO], 1u); break; } } } } while (0)
; __device__ __forceinline__ void xcd_barrier(const XcdBarrier& b, const int tid) {
;     ...
;             const unsigned og = xb_add(&bar[XB_TOP], 1u);
;             const unsigned tg = og / nx;
;             if (og + 1u == (tg + 1u) * nx) xb_add(&bar[XB_TOPGEN], 1u);
;             else XB_SPIN(xb_ld(&bar[XB_TOPGEN]) == tg, bar);
.LBB0_40:
	s_or_b64 exec, exec, s[6:7]
	buffer_inv sc1
	v_cvt_f32_u32_e32 v5, v3
	s_waitcnt vmcnt(0)
	v_readfirstlane_b32 s4, v4
	v_sub_u32_e32 v4, 0, v3
	v_rcp_iflag_f32_e32 v5, v5
	v_add_u32_e32 v6, s4, v1
	v_mul_f32_e32 v5, 0x4f7ffffe, v5
	v_cvt_u32_f32_e32 v5, v5
	v_mul_lo_u32 v1, v4, v5
	v_mul_hi_u32 v1, v5, v1
	v_add_u32_e32 v1, v5, v1
	v_mul_hi_u32 v1, v6, v1
	v_mul_lo_u32 v4, v1, v3
	v_sub_u32_e32 v4, v6, v4
	v_add_u32_e32 v5, 1, v1
	v_cmp_ge_u32_e32 vcc, v4, v3
	s_nop 1
	v_cndmask_b32_e32 v1, v1, v5, vcc
	v_sub_u32_e32 v5, v4, v3
	v_cndmask_b32_e32 v4, v4, v5, vcc
	v_add_u32_e32 v5, 1, v1
	v_cmp_ge_u32_e32 vcc, v4, v3
	v_add_u32_e32 v4, 1, v6
	s_nop 0
	v_cndmask_b32_e32 v1, v1, v5, vcc
	v_mul_lo_u32 v5, v3, v1
	v_add_u32_e32 v3, v5, v3
	v_cmp_ne_u32_e32 vcc, v4, v3
	s_and_saveexec_b64 s[4:5], vcc
	s_xor_b64 s[4:5], exec, s[4:5]
	s_cbranch_execz .LBB0_54
	s_waitcnt lgkmcnt(0)
	v_mov_b32_e32 v2, 0x2000
	global_load_dword v2, v2, s[2:3] offset:1024 sc1
	s_add_u32 s10, s2, 0x2400
	s_addc_u32 s11, s3, 0
	s_waitcnt vmcnt(0)
	v_cmp_eq_u32_e32 vcc, v2, v1
	s_and_saveexec_b64 s[6:7], vcc
	s_cbranch_execz .LBB0_53
	s_add_u32 s8, s22, 0x11d00200
	s_addc_u32 s9, s23, 0
	s_mov_b32 s24, 1
	s_mov_b64 s[12:13], 0
	s_branch .LBB0_44

; __device__ __forceinline__ unsigned xb_ld(unsigned* p)              { return __hip_atomic_load(p, __ATOMIC_RELAXED, __HIP_MEMORY_SCOPE_AGENT); }
; __device__ __forceinline__ unsigned xb_add(unsigned* p, unsigned v) { return __hip_atomic_fetch_add(p, v, __ATOMIC_RELAXED, __HIP_MEMORY_SCOPE_AGENT); }
; #define XB_SPIN(cond, bar) do { unsigned _sp = 0; while (cond) { __builtin_amdgcn_s_sleep(1); \
;     if ((++_sp & 255u) == 0u) { if (xb_ld(&(bar)[XB_TMO])) break; if (_sp > XB_SPIN_CAP) { atomicAdd(&(bar)[XB_TMO], 1u); break; } } } } while (0)
; __device__ __forceinline__ void xcd_barrier(const XcdBarrier& b, const int tid) {
;     ...
;             if (og + 1u == (tg + 1u) * nx) xb_add(&bar[XB_TOPGEN], 1u);
;             else XB_SPIN(xb_ld(&bar[XB_TOPGEN]) == tg, bar);
;             __builtin_amdgcn_fence(__ATOMIC_ACQUIRE, "agent");
;             xb_add(&bar[XB_XGEN(b.x)], 1u);
.LBB0_69:
	s_or_b64 exec, exec, s[6:7]
	s_and_saveexec_b64 s[4:5], s[8:9]
	s_cbranch_execz .LBB0_71
	v_mov_b32_e32 v1, 1
	global_atomic_add v[2:3], v1, off
	v_mov_b32_e32 v4, 0x11d02400
	global_atomic_add v4, v1, s[22:23]
	global_atomic_add v4, v1, s[22:23] offset:256
	global_atomic_add v4, v1, s[22:23] offset:512
	global_atomic_add v4, v1, s[22:23] offset:768
	global_atomic_add v4, v1, s[22:23] offset:1024
	global_atomic_add v4, v1, s[22:23] offset:1280
	global_atomic_add v4, v1, s[22:23] offset:1536
	global_atomic_add v4, v1, s[22:23] offset:1792
	global_atomic_add v4, v1, s[22:23] offset:2048
	global_atomic_add v4, v1, s[22:23] offset:2304
	global_atomic_add v4, v1, s[22:23] offset:2560
	global_atomic_add v4, v1, s[22:23] offset:2816
	global_atomic_add v4, v1, s[22:23] offset:3072
	global_atomic_add v4, v1, s[22:23] offset:3328
	global_atomic_add v4, v1, s[22:23] offset:3584
	global_atomic_add v4, v1, s[22:23] offset:3840
